# compressed-block phase head loop: the head's Q bank is chosen by a scalar branch (no v_swap bank rotation anywhere)
# baseline (speedup 1.0000x reference)
; __device__ __forceinline__ void cmp_phase(LAS unsigned char* lds, const bf16_t* __restrict__ P, const bf16_t* __restrict__ Kc, const bf16_t* __restrict__ Vc,
;                                           bf16_t* __restrict__ ocmp, unsigned long long* __restrict__ mask, int G, const int wave0) {
;     ...
;         for (int hh = 0; hh < 4; ++hh) {
;             const int head = 4 * g + hh;
;             bf16x8 qf[4];
; #pragma unroll
;             for (int ds = 0; ds < 4; ++ds) qf[ds] = *(const bf16x8*)(P + row * NPJ + C_NQ + head * 64 + 16 * ds + 8 * hi);
;             float m_run = -1e30f, l_run = 0.f;
.LBB0_763:
	s_lshl_b32 s6, s9, 6
	s_add_i32 s80, s6, s10
	v_lshl_add_u64 v[0:1], s[80:81], 1, v[86:87]
	s_cmp_lg_u32 s9, 0
	s_cbranch_scc1 .Lhq1
	v_mov_b32_e32 v64, v146
	v_mov_b32_e32 v65, v147
	v_mov_b32_e32 v66, v148
	v_mov_b32_e32 v67, v149
	v_mov_b32_e32 v68, v150
	v_mov_b32_e32 v69, v151
	v_mov_b32_e32 v70, v152
	v_mov_b32_e32 v71, v153
	v_mov_b32_e32 v72, v154
	v_mov_b32_e32 v73, v155
	v_mov_b32_e32 v74, v156
	v_mov_b32_e32 v75, v157
	v_mov_b32_e32 v76, v158
	v_mov_b32_e32 v77, v159
	v_mov_b32_e32 v78, v160
	v_mov_b32_e32 v79, v161
	s_branch .Lhq_done
.Lhq1:
	s_cmp_lg_u32 s9, 1
	s_cbranch_scc1 .Lhq2
	v_mov_b32_e32 v64, v200
	v_mov_b32_e32 v65, v201
	v_mov_b32_e32 v66, v202
	v_mov_b32_e32 v67, v203
	v_mov_b32_e32 v68, v204
	v_mov_b32_e32 v69, v205
	v_mov_b32_e32 v70, v206
	v_mov_b32_e32 v71, v207
	v_mov_b32_e32 v72, v208
	v_mov_b32_e32 v73, v209
	v_mov_b32_e32 v74, v210
	v_mov_b32_e32 v75, v211
	v_mov_b32_e32 v76, v216
	v_mov_b32_e32 v77, v217
	v_mov_b32_e32 v78, v218
	v_mov_b32_e32 v79, v219
	s_branch .Lhq_done
.Lhq2:
	s_cmp_lg_u32 s9, 2
	s_cbranch_scc1 .Lhq3
	v_mov_b32_e32 v64, v220
	v_mov_b32_e32 v65, v221
	v_mov_b32_e32 v66, v222
	v_mov_b32_e32 v67, v223
	v_mov_b32_e32 v68, v224
	v_mov_b32_e32 v69, v225
	v_mov_b32_e32 v70, v226
	v_mov_b32_e32 v71, v227
	v_mov_b32_e32 v72, v228
	v_mov_b32_e32 v73, v229
	v_mov_b32_e32 v74, v230
	v_mov_b32_e32 v75, v231
	v_mov_b32_e32 v76, v232
	v_mov_b32_e32 v77, v233
	v_mov_b32_e32 v78, v234
	v_mov_b32_e32 v79, v235
	s_branch .Lhq_done
.Lhq3:
	v_mov_b32_e32 v64, v130
	v_mov_b32_e32 v65, v131
	v_mov_b32_e32 v66, v132
	v_mov_b32_e32 v67, v133
	v_mov_b32_e32 v68, v134
	v_mov_b32_e32 v69, v135
	v_mov_b32_e32 v70, v136
	v_mov_b32_e32 v71, v137
	v_mov_b32_e32 v72, v138
	v_mov_b32_e32 v73, v139
	v_mov_b32_e32 v74, v140
	v_mov_b32_e32 v75, v141
	v_mov_b32_e32 v76, v142
	v_mov_b32_e32 v77, v143
	v_mov_b32_e32 v78, v144
	v_mov_b32_e32 v79, v145
.Lhq_done:
	v_mov_b32_e32 v33, 0
	v_mov_b32_e32 v34, 0xf149f2ca
	v_mov_b32_e32 v32, v100
	s_mov_b32 s6, 0
